# v55 + first-unit tables (one load round trip, DPP scan, s_bcnt1) + P0 RMSNorm row sums and P4a log-forget scans via DPP instead of ds_bpermute chains
# speedup vs baseline: 1.0107x; 1.0024x over previous
.LBB0_50:
	global_load_dwordx4 v[58:61], v[70:71], off nt
	global_load_dwordx4 v[38:41], v[70:71], off offset:1024 nt
	global_load_dwordx4 v[18:21], v[70:71], off offset:2048 nt
	global_load_dwordx4 v[2:5], v[70:71], off offset:3072 nt
	v_lshl_add_u64 v[10:11], v[70:71], 0, s[20:21]
	v_lshl_add_u64 v[14:15], v[10:11], 0, s[20:21]
	global_load_dwordx4 v[62:65], v[10:11], off nt
	global_load_dwordx4 v[42:45], v[10:11], off offset:1024 nt
	global_load_dwordx4 v[22:25], v[10:11], off offset:2048 nt
	global_load_dwordx4 v[6:9], v[10:11], off offset:3072 nt
	global_load_dwordx4 v[54:57], v[14:15], off nt
	global_load_dwordx4 v[46:49], v[14:15], off offset:1024 nt
	global_load_dwordx4 v[26:29], v[14:15], off offset:2048 nt
	s_nop 0
	global_load_dwordx4 v[10:13], v[14:15], off offset:3072 nt
	v_lshl_add_u64 v[14:15], v[14:15], 0, s[20:21]
	global_load_dwordx4 v[50:53], v[14:15], off nt
	global_load_dwordx4 v[34:37], v[14:15], off offset:1024 nt
	global_load_dwordx4 v[30:33], v[14:15], off offset:2048 nt
	s_nop 0
	global_load_dwordx4 v[14:17], v[14:15], off offset:3072 nt
	s_waitcnt vmcnt(15)
	v_mul_f32_e32 v66, v59, v59
	v_mul_f32_e32 v80, v61, v61
	s_waitcnt vmcnt(14)
	v_mul_f32_e32 v81, v39, v39
	v_mul_f32_e32 v82, v41, v41
	s_waitcnt vmcnt(13)
	v_mul_f32_e32 v84, v19, v19
	v_mul_f32_e32 v86, v21, v21
	v_fmac_f32_e32 v66, v58, v58
	v_fmac_f32_e32 v80, v60, v60
	v_fmac_f32_e32 v81, v38, v38
	v_fmac_f32_e32 v82, v40, v40
	s_waitcnt vmcnt(12)
	v_mul_f32_e32 v92, v3, v3
	v_mul_f32_e32 v93, v5, v5
	v_fmac_f32_e32 v84, v18, v18
	v_fmac_f32_e32 v86, v20, v20
	v_add_f32_e32 v66, v66, v80
	v_add_f32_e32 v80, v81, v82
	v_fmac_f32_e32 v92, v2, v2
	v_fmac_f32_e32 v93, v4, v4
	v_add_f32_e32 v81, v84, v86
	v_add_f32_e32 v66, v66, v80
	v_add_f32_e32 v82, v92, v93
	v_add_f32_e32 v66, v66, v81
	v_add_f32_e32 v66, v66, v82
	s_nop 1
	v_add_f32_dpp v66, v66, v66 row_ror:8 row_mask:0xf bank_mask:0xf
	s_nop 1
	v_add_f32_dpp v66, v66, v66 row_ror:4 row_mask:0xf bank_mask:0xf
	s_nop 1
	v_add_f32_dpp v66, v66, v66 row_ror:2 row_mask:0xf bank_mask:0xf
	s_nop 1
	v_add_f32_dpp v66, v66, v66 row_ror:1 row_mask:0xf bank_mask:0xf
	s_nop 1
	v_add_f32_dpp v66, v66, v66 row_bcast:15 row_mask:0xa bank_mask:0xf
	s_nop 1
	v_add_f32_dpp v66, v66, v66 row_bcast:31 row_mask:0xc bank_mask:0xf
	s_nop 1
	v_readlane_b32 s4, v66, 63
	s_nop 1
	v_mov_b32_e32 v66, s4
	v_fmamk_f32 v66, v66, 0x3a800000, v90
	v_mul_f32_e32 v80, 0x4f800000, v66
	v_cmp_gt_f32_e32 vcc, s13, v66
	s_nop 1
	v_cndmask_b32_e32 v66, v66, v80, vcc
	v_sqrt_f32_e32 v80, v66
	s_nop 0
	v_add_u32_e32 v81, -1, v80
	v_add_u32_e32 v82, 1, v80
	v_fma_f32 v84, -v81, v80, v66
	v_fma_f32 v86, -v82, v80, v66
	v_cmp_ge_f32_e64 s[4:5], 0, v84
	s_nop 1
	v_cndmask_b32_e64 v80, v80, v81, s[4:5]
	v_cmp_lt_f32_e64 s[4:5], 0, v86
	s_nop 1
	v_cndmask_b32_e64 v80, v80, v82, s[4:5]
	v_mul_f32_e32 v81, 0x37800000, v80
	v_cndmask_b32_e32 v80, v80, v81, vcc
	v_cmp_class_f32_e32 vcc, v66, v91
	s_nop 1
	v_cndmask_b32_e32 v86, v80, v66, vcc
	s_and_saveexec_b64 s[4:5], s[0:1]
	s_cbranch_execz .LBB0_52
	s_add_u32 s6, s52, s46
	s_addc_u32 s7, s53, s47
	global_store_dword v67, v86, s[6:7]
.LBB0_52:
	s_or_b64 exec, exec, s[4:5]
	s_waitcnt vmcnt(11)
	v_mul_f32_e32 v66, v63, v63
	v_mul_f32_e32 v80, v65, v65
	v_fmac_f32_e32 v66, v62, v62
	v_fmac_f32_e32 v80, v64, v64
	v_add_f32_e32 v66, v66, v80
	s_waitcnt vmcnt(10)
	v_mul_f32_e32 v80, v43, v43
	v_mul_f32_e32 v81, v45, v45
	v_fmac_f32_e32 v80, v42, v42
	v_fmac_f32_e32 v81, v44, v44
	v_add_f32_e32 v80, v80, v81
	v_add_f32_e32 v66, v66, v80
	s_waitcnt vmcnt(9)
	v_mul_f32_e32 v80, v23, v23
	v_mul_f32_e32 v81, v25, v25
	v_fmac_f32_e32 v80, v22, v22
	v_fmac_f32_e32 v81, v24, v24
	v_add_f32_e32 v80, v80, v81
	v_add_f32_e32 v66, v66, v80
	s_waitcnt vmcnt(8)
	v_mul_f32_e32 v80, v7, v7
	v_mul_f32_e32 v81, v9, v9
	v_fmac_f32_e32 v80, v6, v6
	v_fmac_f32_e32 v81, v8, v8
	v_add_f32_e32 v80, v80, v81
	v_add_f32_e32 v66, v66, v80
	s_nop 1
	v_add_f32_dpp v66, v66, v66 row_ror:8 row_mask:0xf bank_mask:0xf
	s_nop 1
	v_add_f32_dpp v66, v66, v66 row_ror:4 row_mask:0xf bank_mask:0xf
	s_nop 1
	v_add_f32_dpp v66, v66, v66 row_ror:2 row_mask:0xf bank_mask:0xf
	s_nop 1
	v_add_f32_dpp v66, v66, v66 row_ror:1 row_mask:0xf bank_mask:0xf
	s_nop 1
	v_add_f32_dpp v66, v66, v66 row_bcast:15 row_mask:0xa bank_mask:0xf
	s_nop 1
	v_add_f32_dpp v66, v66, v66 row_bcast:31 row_mask:0xc bank_mask:0xf
	s_nop 1
	v_readlane_b32 s4, v66, 63
	s_nop 1
	v_mov_b32_e32 v66, s4
	v_fmamk_f32 v66, v66, 0x3a800000, v90
	v_mul_f32_e32 v80, 0x4f800000, v66
	v_cmp_gt_f32_e32 vcc, s13, v66
	s_nop 1
	v_cndmask_b32_e32 v66, v66, v80, vcc
	v_sqrt_f32_e32 v80, v66
	s_nop 0
	v_add_u32_e32 v81, -1, v80
	v_add_u32_e32 v82, 1, v80
	v_fma_f32 v84, -v81, v80, v66
	v_fma_f32 v92, -v82, v80, v66
	v_cmp_ge_f32_e64 s[4:5], 0, v84
	s_nop 1
	v_cndmask_b32_e64 v80, v80, v81, s[4:5]
	v_cmp_lt_f32_e64 s[4:5], 0, v92
	s_nop 1
	v_cndmask_b32_e64 v80, v80, v82, s[4:5]
	v_mul_f32_e32 v81, 0x37800000, v80
	v_cndmask_b32_e32 v80, v80, v81, vcc
	v_cmp_class_f32_e32 vcc, v66, v91
	s_nop 1
	v_cndmask_b32_e32 v84, v80, v66, vcc
	s_and_saveexec_b64 s[4:5], s[0:1]
	s_cbranch_execz .LBB0_54
	s_add_u32 s6, s52, s48
	s_addc_u32 s7, s53, s49
	global_store_dword v67, v84, s[6:7]
.LBB0_54:
	s_or_b64 exec, exec, s[4:5]
	s_waitcnt vmcnt(7)
	v_mul_f32_e32 v66, v55, v55
	v_mul_f32_e32 v80, v57, v57
	v_fmac_f32_e32 v66, v54, v54
	v_fmac_f32_e32 v80, v56, v56
	v_add_f32_e32 v66, v66, v80
	s_waitcnt vmcnt(6)
	v_mul_f32_e32 v80, v47, v47
	v_mul_f32_e32 v81, v49, v49
	v_fmac_f32_e32 v80, v46, v46
	v_fmac_f32_e32 v81, v48, v48
	v_add_f32_e32 v80, v80, v81
	v_add_f32_e32 v66, v66, v80
	s_waitcnt vmcnt(5)
	v_mul_f32_e32 v80, v27, v27
	v_mul_f32_e32 v81, v29, v29
	v_fmac_f32_e32 v80, v26, v26
	v_fmac_f32_e32 v81, v28, v28
	v_add_f32_e32 v80, v80, v81
	v_add_f32_e32 v66, v66, v80
	s_waitcnt vmcnt(4)
	v_mul_f32_e32 v80, v11, v11
	v_mul_f32_e32 v81, v13, v13
	v_fmac_f32_e32 v80, v10, v10
	v_fmac_f32_e32 v81, v12, v12
	v_add_f32_e32 v80, v80, v81
	v_add_f32_e32 v66, v66, v80
	s_nop 1
	v_add_f32_dpp v66, v66, v66 row_ror:8 row_mask:0xf bank_mask:0xf
	s_nop 1
	v_add_f32_dpp v66, v66, v66 row_ror:4 row_mask:0xf bank_mask:0xf
	s_nop 1
	v_add_f32_dpp v66, v66, v66 row_ror:2 row_mask:0xf bank_mask:0xf
	s_nop 1
	v_add_f32_dpp v66, v66, v66 row_ror:1 row_mask:0xf bank_mask:0xf
	s_nop 1
	v_add_f32_dpp v66, v66, v66 row_bcast:15 row_mask:0xa bank_mask:0xf
	s_nop 1
	v_add_f32_dpp v66, v66, v66 row_bcast:31 row_mask:0xc bank_mask:0xf
	s_nop 1
	v_readlane_b32 s4, v66, 63
	s_nop 1
	v_mov_b32_e32 v66, s4
	v_fmamk_f32 v66, v66, 0x3a800000, v90
	v_mul_f32_e32 v80, 0x4f800000, v66
	v_cmp_gt_f32_e32 vcc, s13, v66
	s_nop 1
	v_cndmask_b32_e32 v66, v66, v80, vcc
	v_sqrt_f32_e32 v80, v66
	s_nop 0
	v_add_u32_e32 v81, -1, v80
	v_add_u32_e32 v82, 1, v80
	v_fma_f32 v92, -v81, v80, v66
	v_fma_f32 v93, -v82, v80, v66
	v_cmp_ge_f32_e64 s[4:5], 0, v92
	s_nop 1
	v_cndmask_b32_e64 v80, v80, v81, s[4:5]
	v_cmp_lt_f32_e64 s[4:5], 0, v93
	s_nop 1
	v_cndmask_b32_e64 v80, v80, v82, s[4:5]
	v_mul_f32_e32 v81, 0x37800000, v80
	v_cndmask_b32_e32 v80, v80, v81, vcc
	v_cmp_class_f32_e32 vcc, v66, v91
	s_nop 1
	v_cndmask_b32_e32 v82, v80, v66, vcc
	s_and_saveexec_b64 s[4:5], s[0:1]
	s_cbranch_execz .LBB0_56
	s_add_u32 s6, s52, s56
	s_addc_u32 s7, s53, s57
	global_store_dword v67, v82, s[6:7]
.LBB0_56:
	s_or_b64 exec, exec, s[4:5]
	s_waitcnt vmcnt(3)
	v_mul_f32_e32 v66, v51, v51
	v_mul_f32_e32 v80, v53, v53
	v_fmac_f32_e32 v66, v50, v50
	v_fmac_f32_e32 v80, v52, v52
	v_add_f32_e32 v66, v66, v80
	s_waitcnt vmcnt(2)
	v_mul_f32_e32 v80, v35, v35
	v_mul_f32_e32 v81, v37, v37
	v_fmac_f32_e32 v80, v34, v34
	v_fmac_f32_e32 v81, v36, v36
	v_add_f32_e32 v80, v80, v81
	v_add_f32_e32 v66, v66, v80
	s_waitcnt vmcnt(1)
	v_mul_f32_e32 v80, v31, v31
	v_mul_f32_e32 v81, v33, v33
	v_fmac_f32_e32 v80, v30, v30
	v_fmac_f32_e32 v81, v32, v32
	v_add_f32_e32 v80, v80, v81
	v_add_f32_e32 v66, v66, v80
	s_waitcnt vmcnt(0)
	v_mul_f32_e32 v80, v15, v15
	v_mul_f32_e32 v81, v17, v17
	v_fmac_f32_e32 v80, v14, v14
	v_fmac_f32_e32 v81, v16, v16
	v_add_f32_e32 v80, v80, v81
	v_add_f32_e32 v66, v66, v80
	s_nop 1
	v_add_f32_dpp v66, v66, v66 row_ror:8 row_mask:0xf bank_mask:0xf
	s_nop 1
	v_add_f32_dpp v66, v66, v66 row_ror:4 row_mask:0xf bank_mask:0xf
	s_nop 1
	v_add_f32_dpp v66, v66, v66 row_ror:2 row_mask:0xf bank_mask:0xf
	s_nop 1
	v_add_f32_dpp v66, v66, v66 row_ror:1 row_mask:0xf bank_mask:0xf
	s_nop 1
	v_add_f32_dpp v66, v66, v66 row_bcast:15 row_mask:0xa bank_mask:0xf
	s_nop 1
	v_add_f32_dpp v66, v66, v66 row_bcast:31 row_mask:0xc bank_mask:0xf
	s_nop 1
	v_readlane_b32 s4, v66, 63
	s_nop 1
	v_mov_b32_e32 v66, s4
	v_fmamk_f32 v66, v66, 0x3a800000, v90
	v_mul_f32_e32 v80, 0x4f800000, v66
	v_cmp_gt_f32_e32 vcc, s13, v66
	s_nop 1
	v_cndmask_b32_e32 v66, v66, v80, vcc
	v_sqrt_f32_e32 v80, v66
	s_nop 0
	v_add_u32_e32 v81, -1, v80
	v_add_u32_e32 v92, 1, v80
	v_fma_f32 v93, -v81, v80, v66
	v_fma_f32 v94, -v92, v80, v66
	v_cmp_ge_f32_e64 s[4:5], 0, v93
	s_nop 1
	v_cndmask_b32_e64 v80, v80, v81, s[4:5]
	v_cmp_lt_f32_e64 s[4:5], 0, v94
	s_nop 1
	v_cndmask_b32_e64 v80, v80, v92, s[4:5]
	v_mul_f32_e32 v81, 0x37800000, v80
	v_cndmask_b32_e32 v80, v80, v81, vcc
	v_cmp_class_f32_e32 vcc, v66, v91
	s_nop 1
	v_cndmask_b32_e32 v66, v80, v66, vcc
	s_and_saveexec_b64 s[4:5], s[0:1]
	s_cbranch_execz .LBB0_49
	s_add_u32 s6, s52, s60
	s_addc_u32 s7, s53, s61
	global_store_dword v67, v66, s[6:7]
	s_branch .LBB0_49

.LBB0_351:
	global_load_dword v100, v1, s[42:43]
	global_load_dword v101, v1, s[42:43] offset:4
	v_add_u32_e32 v10, s15, v171
	v_add_u32_e32 v34, 16, v10
	v_add_u32_e32 v38, 32, v10
	v_ashrrev_i32_e32 v11, 31, v10
	v_ashrrev_i32_e32 v35, 31, v34
	v_ashrrev_i32_e32 v39, 31, v38
	v_lshlrev_b64 v[50:51], 11, v[10:11]
	v_lshlrev_b64 v[54:55], 11, v[34:35]
	v_lshlrev_b64 v[58:59], 11, v[38:39]
	v_lshl_add_u64 v[30:31], v[4:5], 0, v[50:51]
	v_lshl_add_u64 v[34:35], v[4:5], 0, v[54:55]
	v_lshl_add_u64 v[38:39], v[4:5], 0, v[58:59]
	global_load_dwordx4 v[26:29], v[2:3], off
	v_add_u32_e32 v10, 48, v10
	global_load_dwordx4 v[30:33], v[30:31], off
	v_ashrrev_i32_e32 v11, 31, v10
	global_load_dwordx4 v[34:37], v[34:35], off
	v_lshlrev_b64 v[10:11], 11, v[10:11]
	global_load_dwordx4 v[38:41], v[38:39], off
	v_lshl_add_u64 v[42:43], v[4:5], 0, v[10:11]
	global_load_dwordx4 v[42:45], v[42:43], off
	s_nop 0
	global_load_dwordx4 v[46:49], v[2:3], off offset:64
	v_lshl_add_u64 v[66:67], s[36:37], 0, v[50:51]
	v_lshl_add_u64 v[68:69], s[36:37], 0, v[54:55]
	v_lshl_add_u64 v[50:51], v[66:67], 0, v[0:1]
	v_lshl_add_u64 v[54:55], v[68:69], 0, v[0:1]
	v_lshl_add_u64 v[70:71], s[36:37], 0, v[58:59]
	global_load_dwordx4 v[50:53], v[50:51], off
	v_lshl_add_u64 v[58:59], v[70:71], 0, v[0:1]
	global_load_dwordx4 v[54:57], v[54:55], off
	v_lshl_add_u64 v[10:11], s[36:37], 0, v[10:11]
	global_load_dwordx4 v[58:61], v[58:59], off
	v_lshl_add_u64 v[62:63], v[10:11], 0, v[0:1]
	v_lshl_add_u64 v[72:73], v[68:69], 0, v[6:7]
	s_waitcnt vmcnt(7)
	v_mfma_f32_16x16x32_bf16 v[30:33], v[30:33], v[26:29], 0
	s_waitcnt vmcnt(6)
	v_mfma_f32_16x16x32_bf16 v[34:37], v[34:37], v[26:29], 0
	s_waitcnt vmcnt(5)
	v_mfma_f32_16x16x32_bf16 v[38:41], v[38:41], v[26:29], 0
	s_waitcnt vmcnt(4)
	v_mfma_f32_16x16x32_bf16 v[26:29], v[42:45], v[26:29], 0
	global_load_dwordx4 v[42:45], v[62:63], off
	v_lshl_add_u64 v[62:63], v[66:67], 0, v[6:7]
	v_lshl_add_u64 v[66:67], v[66:67], 0, v[8:9]
	s_waitcnt vmcnt(3)
	v_mfma_f32_16x16x32_bf16 v[30:33], v[50:53], v[46:49], v[30:33]
	global_load_dwordx4 v[50:53], v[62:63], off
	s_nop 0
	global_load_dwordx4 v[62:65], v[2:3], off offset:128
	s_waitcnt vmcnt(4)
	v_mfma_f32_16x16x32_bf16 v[34:37], v[54:57], v[46:49], v[34:37]
	global_load_dwordx4 v[54:57], v[72:73], off
	v_lshl_add_u64 v[72:73], v[70:71], 0, v[6:7]
	s_waitcnt vmcnt(4)
	v_mfma_f32_16x16x32_bf16 v[38:41], v[58:61], v[46:49], v[38:41]
	global_load_dwordx4 v[58:61], v[72:73], off
	v_lshl_add_u64 v[72:73], v[10:11], 0, v[6:7]
	v_lshl_add_u64 v[10:11], v[10:11], 0, v[8:9]
	s_waitcnt vmcnt(2)
	v_mfma_f32_16x16x32_bf16 v[30:33], v[50:53], v[62:65], v[30:33]
	v_mfma_f32_16x16x32_bf16 v[26:29], v[42:45], v[46:49], v[26:29]
	global_load_dwordx4 v[42:45], v[72:73], off
	global_load_dwordx4 v[46:49], v[2:3], off offset:192
	global_load_dwordx4 v[50:53], v[66:67], off
	s_waitcnt vmcnt(4)
	v_mfma_f32_16x16x32_bf16 v[34:37], v[54:57], v[62:65], v[34:37]
	s_waitcnt vmcnt(3)
	v_mfma_f32_16x16x32_bf16 v[38:41], v[58:61], v[62:65], v[38:41]
	s_waitcnt vmcnt(2)
	v_mfma_f32_16x16x32_bf16 v[26:29], v[42:45], v[62:65], v[26:29]
	global_load_dwordx4 v[42:45], v[10:11], off
	v_lshl_add_u64 v[66:67], v[68:69], 0, v[8:9]
	global_load_dwordx4 v[54:57], v[66:67], off
	v_lshl_add_u64 v[66:67], v[70:71], 0, v[8:9]
	global_load_dwordx4 v[58:61], v[66:67], off
	v_add_u32_e32 v10, s15, v204
	v_ashrrev_i32_e32 v11, 31, v10
	s_waitcnt vmcnt(3)
	v_mfma_f32_16x16x32_bf16 v[30:33], v[50:53], v[46:49], v[30:33]
	v_lshlrev_b64 v[50:51], 6, v[10:11]
	v_lshl_add_u64 v[66:67], s[60:61], 0, v[50:51]
	global_load_dwordx4 v[50:53], v[66:67], off
	v_lshl_add_u64 v[10:11], v[10:11], 2, s[38:39]
	s_waitcnt vmcnt(3)
	v_mfma_f32_16x16x32_bf16 v[26:29], v[42:45], v[46:49], v[26:29]
	s_waitcnt vmcnt(0)
	v_add_f32_e32 v25, v50, v51
	v_mfma_f32_16x16x32_bf16 v[34:37], v[54:57], v[46:49], v[34:37]
	global_load_dwordx4 v[54:57], v[66:67], off offset:16
	global_load_dwordx4 v[62:65], v[66:67], off offset:32
	v_mfma_f32_16x16x32_bf16 v[38:41], v[58:61], v[46:49], v[38:41]
	global_load_dwordx4 v[58:61], v[66:67], off offset:48
	ds_write2_b32 v19, v30, v31 offset1:16
	ds_write2_b32 v19, v32, v33 offset0:32 offset1:48
	s_nop 1
	ds_write2_b32 v22, v34, v35 offset1:16
	ds_write2_b32 v22, v36, v37 offset0:32 offset1:48
	s_nop 0
	ds_write2_b32 v23, v38, v39 offset1:16
	ds_write2_b32 v23, v40, v41 offset0:32 offset1:48
	ds_write2_b32 v24, v26, v27 offset1:16
	ds_write2_b32 v24, v28, v29 offset0:32 offset1:48
	s_waitcnt lgkmcnt(0)
	s_barrier
	v_mov_b32_e32 v34, v100
	v_add_f32_e32 v26, v52, v53
	v_add_f32_e32 v25, v25, v26
	s_waitcnt vmcnt(2)
	v_add_f32_e32 v27, v54, v55
	v_add_f32_e32 v28, v56, v57
	s_waitcnt vmcnt(1)
	v_add_f32_e32 v29, v62, v63
	v_add_f32_e32 v30, v64, v65
	v_add_f32_e32 v26, v27, v28
	s_waitcnt vmcnt(0)
	v_add_f32_e32 v31, v58, v59
	v_add_f32_e32 v32, v60, v61
	v_add_f32_e32 v27, v29, v30
	v_add_f32_e32 v25, v25, v26
	v_add_f32_e32 v28, v31, v32
	v_add_f32_e32 v25, v25, v27
	v_add_f32_e32 v25, v25, v28
	v_fmamk_f32 v25, v25, 0x3a800000, v20
	v_mul_f32_e32 v26, 0x4f800000, v25
	v_cmp_gt_f32_e32 vcc, s57, v25
	s_nop 1
	v_cndmask_b32_e32 v25, v25, v26, vcc
	v_sqrt_f32_e32 v26, v25
	s_nop 0
	v_add_u32_e32 v27, -1, v26
	v_add_u32_e32 v28, 1, v26
	v_fma_f32 v29, -v27, v26, v25
	v_fma_f32 v30, -v28, v26, v25
	v_cmp_ge_f32_e64 s[22:23], 0, v29
	s_nop 1
	v_cndmask_b32_e64 v26, v26, v27, s[22:23]
	v_cmp_lt_f32_e64 s[22:23], 0, v30
	s_nop 1
	v_cndmask_b32_e64 v26, v26, v28, s[22:23]
	v_mul_f32_e32 v27, 0x37800000, v26
	v_cndmask_b32_e32 v26, v26, v27, vcc
	v_cmp_class_f32_e32 vcc, v25, v21
	s_nop 1
	v_cndmask_b32_e32 v25, v26, v25, vcc
	v_div_scale_f32 v35, s[22:23], v25, v25, 1.0
	v_rcp_f32_e32 v37, v35
	ds_read2st64_b32 v[26:27], v12 offset1:16
	ds_read2st64_b32 v[28:29], v12 offset0:32 offset1:48
	ds_read2st64_b32 v[30:31], v12 offset0:64 offset1:80
	ds_read2st64_b32 v[32:33], v12 offset0:96 offset1:112
	v_div_scale_f32 v36, vcc, 1.0, v25, 1.0
	v_fma_f32 v38, -v35, v37, 1.0
	s_waitcnt lgkmcnt(3)
	v_add_f32_e32 v26, 0, v26
	v_fmac_f32_e32 v37, v38, v37
	v_add_f32_e32 v26, v26, v27
	v_mul_f32_e32 v38, v36, v37
	s_waitcnt lgkmcnt(2)
	v_add_f32_e32 v26, v26, v28
	v_fma_f32 v39, -v35, v38, v36
	v_add_f32_e32 v26, v26, v29
	v_fmac_f32_e32 v38, v39, v37
	s_waitcnt lgkmcnt(1)
	v_add_f32_e32 v26, v26, v30
	v_fma_f32 v27, -v35, v38, v36
	v_add_f32_e32 v26, v26, v31
	v_div_fmas_f32 v27, v27, v37, v38
	s_waitcnt lgkmcnt(0)
	v_add_f32_e32 v26, v26, v32
	v_div_fixup_f32 v25, v27, v25, 1.0
	v_add_f32_e32 v26, v26, v33
	s_waitcnt vmcnt(0)
	v_fmac_f32_e32 v34, v25, v26
	v_mul_f32_e64 v26, |v34|, s64
	v_exp_f32_e32 v26, v26
	v_min_f32_e32 v27, 0, v34
	v_lshl_add_u64 v[28:29], v[10:11], 0, s[46:47]
	v_add_f32_e32 v26, 1.0, v26
	v_log_f32_e32 v26, v26
	s_nop 0
	v_fmac_f32_e32 v27, 0xbf317218, v26
	s_nop 1
	v_add_f32_dpp v27, v27, v27 row_shr:1 row_mask:0xf bank_mask:0xf
	s_nop 1
	v_add_f32_dpp v27, v27, v27 row_shr:2 row_mask:0xf bank_mask:0xf
	s_nop 1
	v_add_f32_dpp v27, v27, v27 row_shr:4 row_mask:0xf bank_mask:0xf
	s_nop 1
	v_add_f32_dpp v27, v27, v27 row_shr:8 row_mask:0xf bank_mask:0xf
	s_nop 1
	v_add_f32_dpp v27, v27, v27 row_bcast:15 row_mask:0xa bank_mask:0xf
	s_nop 1
	v_add_f32_dpp v27, v27, v27 row_bcast:31 row_mask:0xc bank_mask:0xf
	v_mov_b32_e32 v26, v27
	global_store_dword v[28:29], v27, off sc1
	s_and_saveexec_b64 s[22:23], s[0:1]
	s_cbranch_execz .LBB0_353
	s_add_i32 s44, s14, s65
	s_ashr_i32 s45, s44, 31
	s_lshl_b64 s[44:45], s[44:45], 2
	s_add_u32 s44, s74, s44
	s_addc_u32 s45, s75, s45
	global_store_dword v1, v26, s[44:45] sc1
.LBB0_353:
	s_or_b64 exec, exec, s[22:23]
	v_mov_b32_e32 v34, v101
	v_add_u32_e32 v32, 4, v12
	ds_read2st64_b32 v[26:27], v32 offset1:16
	ds_read2st64_b32 v[28:29], v32 offset0:32 offset1:48
	ds_read2st64_b32 v[30:31], v32 offset0:64 offset1:80
	ds_read2st64_b32 v[32:33], v32 offset0:96 offset1:112
	v_lshl_add_u64 v[10:11], v[10:11], 0, s[48:49]
	s_waitcnt lgkmcnt(3)
	v_add_f32_e32 v26, 0, v26
	v_add_f32_e32 v26, v26, v27
	s_waitcnt lgkmcnt(2)
	v_add_f32_e32 v26, v26, v28
	v_add_f32_e32 v26, v26, v29
	s_waitcnt lgkmcnt(1)
	v_add_f32_e32 v26, v26, v30
	v_add_f32_e32 v26, v26, v31
	s_waitcnt lgkmcnt(0)
	v_add_f32_e32 v26, v26, v32
	v_add_f32_e32 v26, v26, v33
	v_fmac_f32_e32 v34, v25, v26
	v_mul_f32_e64 v25, |v34|, s64
	v_exp_f32_e32 v25, v25
	v_min_f32_e32 v26, 0, v34
	v_add_f32_e32 v25, 1.0, v25
	v_log_f32_e32 v25, v25
	s_nop 0
	v_fmac_f32_e32 v26, 0xbf317218, v25
	s_nop 1
	v_add_f32_dpp v26, v26, v26 row_shr:1 row_mask:0xf bank_mask:0xf
	s_nop 1
	v_add_f32_dpp v26, v26, v26 row_shr:2 row_mask:0xf bank_mask:0xf
	s_nop 1
	v_add_f32_dpp v26, v26, v26 row_shr:4 row_mask:0xf bank_mask:0xf
	s_nop 1
	v_add_f32_dpp v26, v26, v26 row_shr:8 row_mask:0xf bank_mask:0xf
	s_nop 1
	v_add_f32_dpp v26, v26, v26 row_bcast:15 row_mask:0xa bank_mask:0xf
	s_nop 1
	v_add_f32_dpp v26, v26, v26 row_bcast:31 row_mask:0xc bank_mask:0xf
	v_mov_b32_e32 v25, v26
	global_store_dword v[10:11], v26, off sc1
	s_and_saveexec_b64 s[22:23], s[0:1]
	s_cbranch_execz .LBB0_350
	s_add_i32 s33, s14, s65
	s_add_i32 s44, s33, 0x100
	s_ashr_i32 s45, s44, 31
	s_lshl_b64 s[44:45], s[44:45], 2
	s_add_u32 s44, s74, s44
	s_addc_u32 s45, s75, s45
	global_store_dword v1, v25, s[44:45] sc1
	s_branch .LBB0_350

.LBB0_443:
	global_load_dword v100, v1, s[40:41]
	global_load_dword v101, v1, s[40:41] offset:4
	v_add_u32_e32 v10, s15, v171
	v_add_u32_e32 v34, 16, v10
	v_add_u32_e32 v38, 32, v10
	v_ashrrev_i32_e32 v11, 31, v10
	v_ashrrev_i32_e32 v35, 31, v34
	v_ashrrev_i32_e32 v39, 31, v38
	v_lshlrev_b64 v[50:51], 11, v[10:11]
	v_lshlrev_b64 v[54:55], 11, v[34:35]
	v_lshlrev_b64 v[58:59], 11, v[38:39]
	v_lshl_add_u64 v[30:31], v[4:5], 0, v[50:51]
	v_lshl_add_u64 v[34:35], v[4:5], 0, v[54:55]
	v_lshl_add_u64 v[38:39], v[4:5], 0, v[58:59]
	global_load_dwordx4 v[26:29], v[2:3], off
	v_add_u32_e32 v10, 48, v10
	global_load_dwordx4 v[30:33], v[30:31], off
	v_ashrrev_i32_e32 v11, 31, v10
	global_load_dwordx4 v[34:37], v[34:35], off
	v_lshlrev_b64 v[10:11], 11, v[10:11]
	global_load_dwordx4 v[38:41], v[38:39], off
	v_lshl_add_u64 v[42:43], v[4:5], 0, v[10:11]
	global_load_dwordx4 v[42:45], v[42:43], off
	s_nop 0
	global_load_dwordx4 v[46:49], v[2:3], off offset:64
	v_lshl_add_u64 v[66:67], s[36:37], 0, v[50:51]
	v_lshl_add_u64 v[68:69], s[36:37], 0, v[54:55]
	v_lshl_add_u64 v[50:51], v[66:67], 0, v[0:1]
	v_lshl_add_u64 v[54:55], v[68:69], 0, v[0:1]
	v_lshl_add_u64 v[70:71], s[36:37], 0, v[58:59]
	global_load_dwordx4 v[50:53], v[50:51], off
	v_lshl_add_u64 v[58:59], v[70:71], 0, v[0:1]
	global_load_dwordx4 v[54:57], v[54:55], off
	v_lshl_add_u64 v[10:11], s[36:37], 0, v[10:11]
	global_load_dwordx4 v[58:61], v[58:59], off
	v_lshl_add_u64 v[62:63], v[10:11], 0, v[0:1]
	v_lshl_add_u64 v[72:73], v[68:69], 0, v[6:7]
	s_waitcnt vmcnt(7)
	v_mfma_f32_16x16x32_bf16 v[30:33], v[30:33], v[26:29], 0
	s_waitcnt vmcnt(6)
	v_mfma_f32_16x16x32_bf16 v[34:37], v[34:37], v[26:29], 0
	s_waitcnt vmcnt(5)
	v_mfma_f32_16x16x32_bf16 v[38:41], v[38:41], v[26:29], 0
	s_waitcnt vmcnt(4)
	v_mfma_f32_16x16x32_bf16 v[26:29], v[42:45], v[26:29], 0
	global_load_dwordx4 v[42:45], v[62:63], off
	v_lshl_add_u64 v[62:63], v[66:67], 0, v[6:7]
	v_lshl_add_u64 v[66:67], v[66:67], 0, v[8:9]
	s_waitcnt vmcnt(3)
	v_mfma_f32_16x16x32_bf16 v[30:33], v[50:53], v[46:49], v[30:33]
	global_load_dwordx4 v[50:53], v[62:63], off
	s_nop 0
	global_load_dwordx4 v[62:65], v[2:3], off offset:128
	s_waitcnt vmcnt(4)
	v_mfma_f32_16x16x32_bf16 v[34:37], v[54:57], v[46:49], v[34:37]
	global_load_dwordx4 v[54:57], v[72:73], off
	v_lshl_add_u64 v[72:73], v[70:71], 0, v[6:7]
	s_waitcnt vmcnt(4)
	v_mfma_f32_16x16x32_bf16 v[38:41], v[58:61], v[46:49], v[38:41]
	global_load_dwordx4 v[58:61], v[72:73], off
	v_lshl_add_u64 v[72:73], v[10:11], 0, v[6:7]
	v_lshl_add_u64 v[10:11], v[10:11], 0, v[8:9]
	s_waitcnt vmcnt(2)
	v_mfma_f32_16x16x32_bf16 v[30:33], v[50:53], v[62:65], v[30:33]
	v_mfma_f32_16x16x32_bf16 v[26:29], v[42:45], v[46:49], v[26:29]
	global_load_dwordx4 v[42:45], v[72:73], off
	global_load_dwordx4 v[46:49], v[2:3], off offset:192
	global_load_dwordx4 v[50:53], v[66:67], off
	s_waitcnt vmcnt(4)
	v_mfma_f32_16x16x32_bf16 v[34:37], v[54:57], v[62:65], v[34:37]
	s_waitcnt vmcnt(3)
	v_mfma_f32_16x16x32_bf16 v[38:41], v[58:61], v[62:65], v[38:41]
	s_waitcnt vmcnt(2)
	v_mfma_f32_16x16x32_bf16 v[26:29], v[42:45], v[62:65], v[26:29]
	global_load_dwordx4 v[42:45], v[10:11], off
	v_lshl_add_u64 v[66:67], v[68:69], 0, v[8:9]
	global_load_dwordx4 v[54:57], v[66:67], off
	v_lshl_add_u64 v[66:67], v[70:71], 0, v[8:9]
	global_load_dwordx4 v[58:61], v[66:67], off
	v_add_u32_e32 v10, s15, v204
	v_ashrrev_i32_e32 v11, 31, v10
	s_waitcnt vmcnt(3)
	v_mfma_f32_16x16x32_bf16 v[30:33], v[50:53], v[46:49], v[30:33]
	v_lshlrev_b64 v[50:51], 6, v[10:11]
	v_lshl_add_u64 v[66:67], s[60:61], 0, v[50:51]
	global_load_dwordx4 v[50:53], v[66:67], off
	v_lshl_add_u64 v[10:11], v[10:11], 2, s[38:39]
	s_waitcnt vmcnt(3)
	v_mfma_f32_16x16x32_bf16 v[26:29], v[42:45], v[46:49], v[26:29]
	s_waitcnt vmcnt(0)
	v_add_f32_e32 v25, v50, v51
	v_mfma_f32_16x16x32_bf16 v[34:37], v[54:57], v[46:49], v[34:37]
	global_load_dwordx4 v[54:57], v[66:67], off offset:16
	global_load_dwordx4 v[62:65], v[66:67], off offset:32
	v_mfma_f32_16x16x32_bf16 v[38:41], v[58:61], v[46:49], v[38:41]
	global_load_dwordx4 v[58:61], v[66:67], off offset:48
	ds_write2_b32 v19, v30, v31 offset1:16
	ds_write2_b32 v19, v32, v33 offset0:32 offset1:48
	s_nop 1
	ds_write2_b32 v22, v34, v35 offset1:16
	ds_write2_b32 v22, v36, v37 offset0:32 offset1:48
	s_nop 0
	ds_write2_b32 v23, v38, v39 offset1:16
	ds_write2_b32 v23, v40, v41 offset0:32 offset1:48
	ds_write2_b32 v24, v26, v27 offset1:16
	ds_write2_b32 v24, v28, v29 offset0:32 offset1:48
	s_waitcnt lgkmcnt(0)
	s_barrier
	v_mov_b32_e32 v34, v100
	v_add_f32_e32 v26, v52, v53
	v_add_f32_e32 v25, v25, v26
	s_waitcnt vmcnt(2)
	v_add_f32_e32 v27, v54, v55
	v_add_f32_e32 v28, v56, v57
	s_waitcnt vmcnt(1)
	v_add_f32_e32 v29, v62, v63
	v_add_f32_e32 v30, v64, v65
	v_add_f32_e32 v26, v27, v28
	s_waitcnt vmcnt(0)
	v_add_f32_e32 v31, v58, v59
	v_add_f32_e32 v32, v60, v61
	v_add_f32_e32 v27, v29, v30
	v_add_f32_e32 v25, v25, v26
	v_add_f32_e32 v28, v31, v32
	v_add_f32_e32 v25, v25, v27
	v_add_f32_e32 v25, v25, v28
	v_fmamk_f32 v25, v25, 0x3a800000, v20
	v_mul_f32_e32 v26, 0x4f800000, v25
	v_cmp_gt_f32_e32 vcc, s57, v25
	s_nop 1
	v_cndmask_b32_e32 v25, v25, v26, vcc
	v_sqrt_f32_e32 v26, v25
	s_nop 0
	v_add_u32_e32 v27, -1, v26
	v_add_u32_e32 v28, 1, v26
	v_fma_f32 v29, -v27, v26, v25
	v_fma_f32 v30, -v28, v26, v25
	v_cmp_ge_f32_e64 s[22:23], 0, v29
	s_nop 1
	v_cndmask_b32_e64 v26, v26, v27, s[22:23]
	v_cmp_lt_f32_e64 s[22:23], 0, v30
	s_nop 1
	v_cndmask_b32_e64 v26, v26, v28, s[22:23]
	v_mul_f32_e32 v27, 0x37800000, v26
	v_cndmask_b32_e32 v26, v26, v27, vcc
	v_cmp_class_f32_e32 vcc, v25, v21
	s_nop 1
	v_cndmask_b32_e32 v25, v26, v25, vcc
	v_div_scale_f32 v35, s[22:23], v25, v25, 1.0
	v_rcp_f32_e32 v37, v35
	ds_read2st64_b32 v[26:27], v12 offset1:16
	ds_read2st64_b32 v[28:29], v12 offset0:32 offset1:48
	ds_read2st64_b32 v[30:31], v12 offset0:64 offset1:80
	ds_read2st64_b32 v[32:33], v12 offset0:96 offset1:112
	v_div_scale_f32 v36, vcc, 1.0, v25, 1.0
	v_fma_f32 v38, -v35, v37, 1.0
	s_waitcnt lgkmcnt(3)
	v_add_f32_e32 v26, 0, v26
	v_fmac_f32_e32 v37, v38, v37
	v_add_f32_e32 v26, v26, v27
	v_mul_f32_e32 v38, v36, v37
	s_waitcnt lgkmcnt(2)
	v_add_f32_e32 v26, v26, v28
	v_fma_f32 v39, -v35, v38, v36
	v_add_f32_e32 v26, v26, v29
	v_fmac_f32_e32 v38, v39, v37
	s_waitcnt lgkmcnt(1)
	v_add_f32_e32 v26, v26, v30
	v_fma_f32 v27, -v35, v38, v36
	v_add_f32_e32 v26, v26, v31
	v_div_fmas_f32 v27, v27, v37, v38
	s_waitcnt lgkmcnt(0)
	v_add_f32_e32 v26, v26, v32
	v_div_fixup_f32 v25, v27, v25, 1.0
	v_add_f32_e32 v26, v26, v33
	s_waitcnt vmcnt(0)
	v_fmac_f32_e32 v34, v25, v26
	v_mul_f32_e64 v26, |v34|, s64
	v_exp_f32_e32 v26, v26
	v_min_f32_e32 v27, 0, v34
	v_lshl_add_u64 v[28:29], v[10:11], 0, s[58:59]
	v_add_f32_e32 v26, 1.0, v26
	v_log_f32_e32 v26, v26
	s_nop 0
	v_fmac_f32_e32 v27, 0xbf317218, v26
	s_nop 1
	v_add_f32_dpp v27, v27, v27 row_shr:1 row_mask:0xf bank_mask:0xf
	s_nop 1
	v_add_f32_dpp v27, v27, v27 row_shr:2 row_mask:0xf bank_mask:0xf
	s_nop 1
	v_add_f32_dpp v27, v27, v27 row_shr:4 row_mask:0xf bank_mask:0xf
	s_nop 1
	v_add_f32_dpp v27, v27, v27 row_shr:8 row_mask:0xf bank_mask:0xf
	s_nop 1
	v_add_f32_dpp v27, v27, v27 row_bcast:15 row_mask:0xa bank_mask:0xf
	s_nop 1
	v_add_f32_dpp v27, v27, v27 row_bcast:31 row_mask:0xc bank_mask:0xf
	v_mov_b32_e32 v26, v27
	global_store_dword v[28:29], v27, off sc1
	s_and_saveexec_b64 s[22:23], s[0:1]
	s_cbranch_execz .LBB0_445
	s_add_i32 s66, s14, s65
	s_ashr_i32 s67, s66, 31
	s_lshl_b64 s[66:67], s[66:67], 2
	s_add_u32 s66, s74, s66
	s_addc_u32 s67, s75, s67
	global_store_dword v1, v26, s[66:67] sc1
.LBB0_445:
	s_or_b64 exec, exec, s[22:23]
	v_mov_b32_e32 v34, v101
	v_add_u32_e32 v32, 4, v12
	ds_read2st64_b32 v[26:27], v32 offset1:16
	ds_read2st64_b32 v[28:29], v32 offset0:32 offset1:48
	ds_read2st64_b32 v[30:31], v32 offset0:64 offset1:80
	ds_read2st64_b32 v[32:33], v32 offset0:96 offset1:112
	v_lshl_add_u64 v[10:11], v[10:11], 0, s[62:63]
	s_waitcnt lgkmcnt(3)
	v_add_f32_e32 v26, 0, v26
	v_add_f32_e32 v26, v26, v27
	s_waitcnt lgkmcnt(2)
	v_add_f32_e32 v26, v26, v28
	v_add_f32_e32 v26, v26, v29
	s_waitcnt lgkmcnt(1)
	v_add_f32_e32 v26, v26, v30
	v_add_f32_e32 v26, v26, v31
	s_waitcnt lgkmcnt(0)
	v_add_f32_e32 v26, v26, v32
	v_add_f32_e32 v26, v26, v33
	v_fmac_f32_e32 v34, v25, v26
	v_mul_f32_e64 v25, |v34|, s64
	v_exp_f32_e32 v25, v25
	v_min_f32_e32 v26, 0, v34
	v_add_f32_e32 v25, 1.0, v25
	v_log_f32_e32 v25, v25
	s_nop 0
	v_fmac_f32_e32 v26, 0xbf317218, v25
	s_nop 1
	v_add_f32_dpp v26, v26, v26 row_shr:1 row_mask:0xf bank_mask:0xf
	s_nop 1
	v_add_f32_dpp v26, v26, v26 row_shr:2 row_mask:0xf bank_mask:0xf
	s_nop 1
	v_add_f32_dpp v26, v26, v26 row_shr:4 row_mask:0xf bank_mask:0xf
	s_nop 1
	v_add_f32_dpp v26, v26, v26 row_shr:8 row_mask:0xf bank_mask:0xf
	s_nop 1
	v_add_f32_dpp v26, v26, v26 row_bcast:15 row_mask:0xa bank_mask:0xf
	s_nop 1
	v_add_f32_dpp v26, v26, v26 row_bcast:31 row_mask:0xc bank_mask:0xf
	v_mov_b32_e32 v25, v26
	global_store_dword v[10:11], v26, off sc1
	s_and_saveexec_b64 s[22:23], s[0:1]
	s_cbranch_execz .LBB0_442
	s_add_i32 s33, s14, s65
	s_add_i32 s66, s33, 0x100
	s_ashr_i32 s67, s66, 31
	s_lshl_b64 s[66:67], s[66:67], 2
	s_add_u32 s66, s74, s66
	s_addc_u32 s67, s75, s67
	global_store_dword v1, v25, s[66:67] sc1
	s_branch .LBB0_442

.LBB0_531:
	s_or_b64 exec, exec, s[16:17]
	s_lshl_b32 s16, s15, 2
	v_mov_b32_e32 v23, s16
	global_load_dwordx3 v[20:22], v23, s[20:21]
	s_waitcnt vmcnt(0)
	v_add_f32_e32 v8, v1, v3
	v_add_f32_e32 v9, v8, v5
	v_add_f32_e32 v12, v9, v7
	v_mov_b32_e32 v10, v12
	s_nop 1
	v_add_f32_dpp v10, v10, v10 row_shr:1 row_mask:0xf bank_mask:0xf
	s_nop 1
	v_add_f32_dpp v10, v10, v10 row_shr:2 row_mask:0xf bank_mask:0xf
	s_nop 1
	v_add_f32_dpp v10, v10, v10 row_shr:4 row_mask:0xf bank_mask:0xf
	s_nop 1
	v_add_f32_dpp v10, v10, v10 row_shr:8 row_mask:0xf bank_mask:0xf
	s_nop 1
	v_add_f32_dpp v10, v10, v10 row_bcast:15 row_mask:0xa bank_mask:0xf
	s_nop 1
	v_add_f32_dpp v10, v10, v10 row_bcast:31 row_mask:0xc bank_mask:0xf
	s_nop 0
	v_sub_f32_e32 v15, v10, v12
	v_add_f32_e32 v11, v1, v15
	v_sub_f32_e32 v1, v11, v1
	v_add_f32_e32 v10, v8, v15
	v_cmp_ge_f32_e64 s[16:17], v1, -v197
	s_and_b64 s[16:17], vcc, s[16:17]
	v_sub_f32_e32 v3, v10, v3
	s_bcnt1_i32_b64 s60, s[16:17]
	v_cmp_ge_f32_e64 s[16:17], v3, -v197
	s_and_b64 s[16:17], s[8:9], s[16:17]
	v_add_f32_e32 v9, v9, v15
	s_bcnt1_i32_b64 s61, s[16:17]
	s_add_i32 s60, s60, s61
	v_sub_f32_e32 v3, v9, v5
	v_add_f32_e32 v8, v12, v15
	v_cmp_ge_f32_e64 s[16:17], v3, -v197
	s_and_b64 s[16:17], s[10:11], s[16:17]
	v_sub_f32_e32 v5, v8, v7
	s_bcnt1_i32_b64 s61, s[16:17]
	v_cmp_ge_f32_e64 s[16:17], v5, -v197
	s_and_b64 s[16:17], s[12:13], s[16:17]
	s_add_i32 s60, s60, s61
	s_bcnt1_i32_b64 s61, s[16:17]
	s_add_i32 s60, s60, s61
	s_and_saveexec_b64 s[16:17], vcc
	s_cbranch_execnz .LBB0_695
	s_or_b64 exec, exec, s[16:17]
	s_and_saveexec_b64 s[16:17], s[8:9]
	s_cbranch_execnz .LBB0_696

.LBB0_536:
	s_lshl_b32 s12, s15, 2
	v_mov_b32_e32 v0, s12
	s_waitcnt lgkmcnt(0)
	v_mov_b32_e32 v1, s60
	s_add_i32 s12, s12, 0
	v_sub_u32_e32 v1, s15, v1
	s_add_i32 s12, s12, 0x24800
	s_mov_b64 s[8:9], exec
	v_mov_b32_e32 v0, 0
	s_add_i32 s13, 0, 0x26800
	v_and_b32_e32 v8, -2, v1
	v_mov_b32_e32 v9, s12
	v_mov_b32_e32 v7, s13
	s_waitcnt vmcnt(0)
	v_add_f32_e32 v2, v20, v21
	v_mov_b32_e32 v1, v20
	v_add_f32_e32 v3, v2, v22
	ds_write_b128 v9, v[0:3]
	ds_write_b32 v7, v8
